# pool rewrite + x-row loop de-serialised, padded so all later code keeps the same addresses mod 256 as the pool-only version
# speedup vs baseline: 1.0093x; 1.0093x over previous
; __device__ __forceinline__ unsigned cvt_pk_bf16(float lo, float hi) { unsigned r; asm volatile("v_cvt_pk_bf16_f32 %0, %1, %2" : "=v"(r) : "v"(lo), "v"(hi)); return r; }
; __device__ void phase_prep(float* ldsf) {
;     ...
;     float4 gq[8];
; #pragma unroll
;     for (int i = 0; i < 8; ++i) gq[i] = ((const float4*)g0)[i * 64 + lane];
;     for (int row = blockIdx.x * 8 + wave; row < M_TOK; row += gridDim.x * 8) {
;         const float4* xr = (const float4*)(x + (size_t)row * DM);
;         float4 xv[8];
; #pragma unroll
;         for (int i = 0; i < 8; ++i) xv[i] = xr[i * 64 + lane];
;         float ss = 0.f;
; #pragma unroll
;         for (int i = 0; i < 8; ++i) { const int idx = i * 64 + lane; const float4 v = xv[i];
;             ss += (v.x * v.x + v.y * v.y) + (v.z * v.z + v.w * v.w);
;             u32x2 w; w.x = cvt_pk_bf16(v.x * gq[i].x, v.y * gq[i].y); w.y = cvt_pk_bf16(v.z * gq[i].z, v.w * gq[i].w);
;             *(u32x2*)(hbf + (size_t)row * DM + idx * 4) = w; }
; #pragma unroll
;         for (int o = 32; o >= 1; o >>= 1) ss += __shfl_xor(ss, o);
;         if (lane == 0) rowss[row] = ss;
.LBB0_78:
	s_waitcnt vmcnt(6)
	v_ashrrev_i32_e32 v2, 6, v1
	v_lshl_add_u32 v34, s67, 3, v2
	s_movk_i32 s14, 0x2000
	v_cmp_gt_i32_e32 vcc, s14, v34
	s_and_saveexec_b64 s[14:15], vcc
	s_cbranch_execz .LBB0_83
	v_and_b32_e32 v40, 63, v1
	v_lshlrev_b32_e32 v1, 4, v40
	v_or_b32_e32 v42, 0x100, v40
	global_load_dwordx4 v[2:5], v1, s[10:11]
	global_load_dwordx4 v[6:9], v1, s[10:11] offset:1024
	global_load_dwordx4 v[10:13], v1, s[10:11] offset:2048
	global_load_dwordx4 v[14:17], v1, s[10:11] offset:3072
	v_lshlrev_b32_e32 v1, 4, v42
	v_or_b32_e32 v44, 0x140, v40
	v_or_b32_e32 v46, 0x180, v40
	s_waitcnt vmcnt(4)
	v_lshlrev_b32_e32 v26, 4, v44
	global_load_dwordx4 v[18:21], v1, s[10:11]
	global_load_dwordx4 v[22:25], v26, s[10:11]
	v_lshlrev_b32_e32 v1, 4, v46
	v_or_b32_e32 v48, 0x1c0, v40
	v_lshlrev_b32_e32 v35, 4, v48
	global_load_dwordx4 v[26:29], v1, s[10:11]
	global_load_dwordx4 v[30:33], v35, s[10:11]
	v_mbcnt_lo_u32_b32 v1, -1, 0
	v_mbcnt_hi_u32_b32 v1, -1, v1
	v_mov_b32_e32 v37, 0
	v_lshlrev_b32_e32 v36, 3, v40
	v_and_b32_e32 v35, 64, v1
	v_cmp_eq_u32_e32 vcc, 0, v40
	v_lshl_add_u64 v[38:39], s[4:5], 0, v[36:37]
	s_lshl_b32 s16, s68, 3
	s_mov_b64 s[10:11], 0
	v_lshlrev_b32_e32 v36, 4, v40
	v_lshlrev_b32_e32 v40, 4, v42
	v_lshlrev_b32_e32 v42, 4, v44
	v_lshlrev_b32_e32 v44, 4, v46
	v_lshlrev_b32_e32 v46, 4, v48
	s_movk_i32 s17, 0x1fff
	v_mov_b32_e32 v41, v37
	v_mov_b32_e32 v43, v37
	v_mov_b32_e32 v45, v37
	v_mov_b32_e32 v47, v37
	v_add_u32_e32 v48, 64, v35
	v_xor_b32_e32 v49, 32, v1
	v_xor_b32_e32 v50, 16, v1
	v_xor_b32_e32 v51, 8, v1
	v_xor_b32_e32 v52, 4, v1
	v_xor_b32_e32 v53, 2, v1
	v_xor_b32_e32 v54, 1, v1
	s_cmp_lg_u32 s68, 0x100
	s_cbranch_scc1 .LBB0_81
	s_waitcnt lgkmcnt(0)
	v_add_u32_e32 v220, 0x0, v34
	v_mov_b32_e32 v221, 0
	v_lshlrev_b64 v[56:57], 13, v[220:221]
	v_lshl_add_u64 v[84:85], s[8:9], 0, v[56:57]
	v_lshl_add_u64 v[72:73], v[84:85], 0, v[36:37]
	global_load_dwordx4 v[56:59], v[72:73], off
	global_load_dwordx4 v[60:63], v[72:73], off offset:1024
	global_load_dwordx4 v[64:67], v[72:73], off offset:2048
	global_load_dwordx4 v[68:71], v[72:73], off offset:3072
	v_lshl_add_u64 v[72:73], v[84:85], 0, v[40:41]
	global_load_dwordx4 v[72:75], v[72:73], off
	v_lshl_add_u64 v[76:77], v[84:85], 0, v[42:43]
	global_load_dwordx4 v[76:79], v[76:77], off
	v_lshl_add_u64 v[80:81], v[84:85], 0, v[44:45]
	global_load_dwordx4 v[80:83], v[80:81], off
	v_lshl_add_u64 v[84:85], v[84:85], 0, v[46:47]
	global_load_dwordx4 v[84:87], v[84:85], off
	v_add_u32_e32 v220, 0x800, v34
	v_mov_b32_e32 v221, 0
	v_lshlrev_b64 v[156:157], 13, v[220:221]
	v_lshl_add_u64 v[184:185], s[8:9], 0, v[156:157]
	v_lshl_add_u64 v[172:173], v[184:185], 0, v[36:37]
	global_load_dwordx4 v[156:159], v[172:173], off
	global_load_dwordx4 v[160:163], v[172:173], off offset:1024
	global_load_dwordx4 v[164:167], v[172:173], off offset:2048
	global_load_dwordx4 v[168:171], v[172:173], off offset:3072
	v_lshl_add_u64 v[172:173], v[184:185], 0, v[40:41]
	global_load_dwordx4 v[172:175], v[172:173], off
	v_lshl_add_u64 v[176:177], v[184:185], 0, v[42:43]
	global_load_dwordx4 v[176:179], v[176:177], off
	v_lshl_add_u64 v[180:181], v[184:185], 0, v[44:45]
	global_load_dwordx4 v[180:183], v[180:181], off
	v_lshl_add_u64 v[184:185], v[184:185], 0, v[46:47]
	global_load_dwordx4 v[184:187], v[184:185], off
	v_add_u32_e32 v220, 0x1000, v34
	v_mov_b32_e32 v221, 0
	v_lshlrev_b64 v[188:189], 13, v[220:221]
	v_lshl_add_u64 v[216:217], s[8:9], 0, v[188:189]
	v_lshl_add_u64 v[204:205], v[216:217], 0, v[36:37]
	global_load_dwordx4 v[188:191], v[204:205], off
	global_load_dwordx4 v[192:195], v[204:205], off offset:1024
	global_load_dwordx4 v[196:199], v[204:205], off offset:2048
	global_load_dwordx4 v[200:203], v[204:205], off offset:3072
	v_lshl_add_u64 v[204:205], v[216:217], 0, v[40:41]
	global_load_dwordx4 v[204:207], v[204:205], off
	v_lshl_add_u64 v[208:209], v[216:217], 0, v[42:43]
	global_load_dwordx4 v[208:211], v[208:209], off
	v_lshl_add_u64 v[212:213], v[216:217], 0, v[44:45]
	global_load_dwordx4 v[212:215], v[212:213], off
	v_lshl_add_u64 v[216:217], v[216:217], 0, v[46:47]
	global_load_dwordx4 v[216:219], v[216:217], off
	v_add_u32_e32 v222, 0x0, v34
	v_mov_b32_e32 v223, 0
	v_lshlrev_b64 v[88:89], 12, v[222:223]
	v_lshl_add_u64 v[88:89], v[38:39], 0, v[88:89]
	v_cmp_lt_i32_e64 s[4:5], v49, v48
	s_waitcnt vmcnt(23)
	v_mul_f32_e32 v55, v57, v57
	v_mul_f32_e32 v90, v59, v59
	s_waitcnt vmcnt(22)
	v_mul_f32_e32 v93, v61, v61
	v_mul_f32_e32 v94, v63, v63
	s_waitcnt vmcnt(21)
	v_mul_f32_e32 v97, v65, v65
	v_mul_f32_e32 v98, v67, v67
	v_fmac_f32_e32 v55, v56, v56
	v_fmac_f32_e32 v90, v58, v58
	v_fmac_f32_e32 v93, v60, v60
	v_fmac_f32_e32 v94, v62, v62
	v_mul_f32_e32 v91, v2, v56
	v_mul_f32_e32 v57, v3, v57
	v_mul_f32_e32 v92, v4, v58
	v_mul_f32_e32 v59, v5, v59
	s_waitcnt vmcnt(20)
	v_mul_f32_e32 v101, v69, v69
	v_mul_f32_e32 v102, v71, v71
	v_fmac_f32_e32 v97, v64, v64
	v_fmac_f32_e32 v98, v66, v66
	v_cvt_pk_bf16_f32 v56, v91, v57
	v_add_f32_e32 v55, v55, v90
	v_add_f32_e32 v58, v93, v94
	v_mul_f32_e32 v95, v6, v60
	v_mul_f32_e32 v61, v7, v61
	s_waitcnt vmcnt(19)
	v_mul_f32_e32 v105, v73, v73
	v_mul_f32_e32 v106, v75, v75
	v_fmac_f32_e32 v101, v68, v68
	v_fmac_f32_e32 v102, v70, v70
	v_cvt_pk_bf16_f32 v57, v92, v59
	global_store_dwordx2 v[88:89], v[56:57], off
	v_cvt_pk_bf16_f32 v56, v95, v61
	v_add_f32_e32 v59, v97, v98
	v_add_f32_e32 v55, v55, v58
	v_mul_f32_e32 v96, v8, v62
	v_mul_f32_e32 v63, v9, v63
	v_mul_f32_e32 v99, v10, v64
	v_mul_f32_e32 v65, v11, v65
	s_waitcnt vmcnt(19)
; __device__ __forceinline__ unsigned cvt_pk_bf16(float lo, float hi) { unsigned r; asm volatile("v_cvt_pk_bf16_f32 %0, %1, %2" : "=v"(r) : "v"(lo), "v"(hi)); return r; }
; __device__ void phase_prep(float* ldsf) {
;     ...
;     for (int row = blockIdx.x * 8 + wave; row < M_TOK; row += gridDim.x * 8) {
;         const float4* xr = (const float4*)(x + (size_t)row * DM);
;         float4 xv[8];
; #pragma unroll
;         for (int i = 0; i < 8; ++i) xv[i] = xr[i * 64 + lane];
;         float ss = 0.f;
; #pragma unroll
;         for (int i = 0; i < 8; ++i) { const int idx = i * 64 + lane; const float4 v = xv[i];
;             ss += (v.x * v.x + v.y * v.y) + (v.z * v.z + v.w * v.w);
;             u32x2 w; w.x = cvt_pk_bf16(v.x * gq[i].x, v.y * gq[i].y); w.y = cvt_pk_bf16(v.z * gq[i].z, v.w * gq[i].w);
;             *(u32x2*)(hbf + (size_t)row * DM + idx * 4) = w; }
; #pragma unroll
;         for (int o = 32; o >= 1; o >>= 1) ss += __shfl_xor(ss, o);
;         if (lane == 0) rowss[row] = ss;
	v_mul_f32_e32 v109, v77, v77
	v_mul_f32_e32 v110, v79, v79
	v_fmac_f32_e32 v105, v72, v72
	v_fmac_f32_e32 v106, v74, v74
	v_cvt_pk_bf16_f32 v57, v96, v63
	v_add_f32_e32 v60, v101, v102
	global_store_dwordx2 v[88:89], v[56:57], off offset:512
	v_cvt_pk_bf16_f32 v56, v99, v65
	v_add_f32_e32 v55, v55, v59
	v_mul_f32_e32 v100, v12, v66
	v_mul_f32_e32 v67, v13, v67
	v_mul_f32_e32 v103, v14, v68
	v_mul_f32_e32 v69, v15, v69
	s_waitcnt vmcnt(19)
	v_mul_f32_e32 v111, v81, v81
	v_mul_f32_e32 v112, v83, v83
	v_fmac_f32_e32 v109, v76, v76
	v_fmac_f32_e32 v110, v78, v78
	v_add_f32_e32 v61, v105, v106
	v_cvt_pk_bf16_f32 v57, v100, v67
	global_store_dwordx2 v[88:89], v[56:57], off offset:1024
	v_cvt_pk_bf16_f32 v56, v103, v69
	v_add_f32_e32 v55, v55, v60
	v_mul_f32_e32 v104, v16, v70
	v_mul_f32_e32 v71, v17, v71
	s_waitcnt vmcnt(19)
	v_mul_f32_e32 v113, v85, v85
	v_fmac_f32_e32 v111, v80, v80
	v_fmac_f32_e32 v112, v82, v82
	v_add_f32_e32 v62, v109, v110
	v_cvt_pk_bf16_f32 v57, v104, v71
	global_store_dwordx2 v[88:89], v[56:57], off offset:1536
	v_add_f32_e32 v55, v55, v61
	v_mul_f32_e32 v56, v87, v87
	v_fmac_f32_e32 v113, v84, v84
	v_add_f32_e32 v63, v111, v112
	v_add_f32_e32 v55, v55, v62
	v_fmac_f32_e32 v56, v86, v86
	v_add_f32_e32 v55, v55, v63
	v_add_f32_e32 v56, v113, v56
	v_add_f32_e32 v55, v55, v56
	v_cndmask_b32_e64 v56, v1, v49, s[4:5]
	v_lshlrev_b32_e32 v56, 2, v56
	ds_bpermute_b32 v58, v56, v55
	v_mul_f32_e32 v107, v18, v72
	v_mul_f32_e32 v73, v19, v73
	v_mul_f32_e32 v108, v20, v74
	v_mul_f32_e32 v75, v21, v75
	v_cvt_pk_bf16_f32 v56, v107, v73
	v_cvt_pk_bf16_f32 v57, v108, v75
	v_cmp_lt_i32_e64 s[4:5], v50, v48
	global_store_dwordx2 v[88:89], v[56:57], off offset:2048
	s_waitcnt lgkmcnt(0)
	v_add_f32_e32 v55, v55, v58
	v_cndmask_b32_e64 v57, v1, v50, s[4:5]
	v_lshlrev_b32_e32 v57, 2, v57
	ds_bpermute_b32 v57, v57, v55
	v_cmp_lt_i32_e64 s[4:5], v51, v48
	v_mul_f32_e32 v56, v22, v76
	v_mul_f32_e32 v58, v23, v77
	v_cvt_pk_bf16_f32 v56, v56, v58
	s_waitcnt lgkmcnt(0)
	v_add_f32_e32 v55, v55, v57
	v_cndmask_b32_e64 v57, v1, v51, s[4:5]
	v_lshlrev_b32_e32 v57, 2, v57
	ds_bpermute_b32 v60, v57, v55
	v_mul_f32_e32 v58, v24, v78
	v_cmp_lt_i32_e64 s[4:5], v52, v48
	v_mul_f32_e32 v59, v25, v79
	v_cvt_pk_bf16_f32 v57, v58, v59
	s_waitcnt lgkmcnt(0)
	v_add_f32_e32 v55, v55, v60
	v_cndmask_b32_e64 v58, v1, v52, s[4:5]
	v_lshlrev_b32_e32 v58, 2, v58
	ds_bpermute_b32 v58, v58, v55
	v_cmp_lt_i32_e64 s[4:5], v53, v48
	global_store_dwordx2 v[88:89], v[56:57], off offset:2560
	v_mul_f32_e32 v56, v26, v80
	v_mul_f32_e32 v57, v27, v81
	s_waitcnt lgkmcnt(0)
	v_add_f32_e32 v55, v55, v58
	v_cndmask_b32_e64 v58, v1, v53, s[4:5]
	v_cvt_pk_bf16_f32 v56, v56, v57
	v_mul_f32_e32 v57, v28, v82
	v_mul_f32_e32 v59, v29, v83
	v_lshlrev_b32_e32 v58, 2, v58
	v_cvt_pk_bf16_f32 v57, v57, v59
	ds_bpermute_b32 v59, v58, v55
	global_store_dwordx2 v[88:89], v[56:57], off offset:3072
	v_mul_f32_e32 v56, v30, v84
	v_cmp_lt_i32_e64 s[4:5], v54, v48
	v_mul_f32_e32 v57, v31, v85
	v_cvt_pk_bf16_f32 v58, v56, v57
	s_waitcnt lgkmcnt(0)
	v_add_f32_e32 v55, v55, v59
	v_cndmask_b32_e64 v56, v1, v54, s[4:5]
	v_lshlrev_b32_e32 v56, 2, v56
	ds_bpermute_b32 v56, v56, v55
	v_mul_f32_e32 v59, v33, v87
	v_mul_f32_e32 v57, v32, v86
	v_cvt_pk_bf16_f32 v59, v57, v59
	global_store_dwordx2 v[88:89], v[58:59], off offset:3584
	s_and_saveexec_b64 s[4:5], vcc
	v_lshl_add_u64 v[58:59], v[222:223], 2, s[6:7]
	s_waitcnt lgkmcnt(0)
	v_add_f32_e32 v35, v55, v56
	global_store_dword v[58:59], v35, off
	s_or_b64 exec, exec, s[4:5]
	v_add_u32_e32 v220, 0x1800, v34
	v_mov_b32_e32 v221, 0
	v_lshlrev_b64 v[56:57], 13, v[220:221]
	v_lshl_add_u64 v[84:85], s[8:9], 0, v[56:57]
	v_lshl_add_u64 v[72:73], v[84:85], 0, v[36:37]
	global_load_dwordx4 v[56:59], v[72:73], off
	global_load_dwordx4 v[60:63], v[72:73], off offset:1024
	global_load_dwordx4 v[64:67], v[72:73], off offset:2048
	global_load_dwordx4 v[68:71], v[72:73], off offset:3072
	v_lshl_add_u64 v[72:73], v[84:85], 0, v[40:41]
	global_load_dwordx4 v[72:75], v[72:73], off
	v_lshl_add_u64 v[76:77], v[84:85], 0, v[42:43]
	global_load_dwordx4 v[76:79], v[76:77], off
	v_lshl_add_u64 v[80:81], v[84:85], 0, v[44:45]
	global_load_dwordx4 v[80:83], v[80:81], off
	v_lshl_add_u64 v[84:85], v[84:85], 0, v[46:47]
	global_load_dwordx4 v[84:87], v[84:85], off
	v_add_u32_e32 v222, 0x800, v34
	v_mov_b32_e32 v223, 0
	v_lshlrev_b64 v[88:89], 12, v[222:223]
	v_lshl_add_u64 v[88:89], v[38:39], 0, v[88:89]
	v_cmp_lt_i32_e64 s[4:5], v49, v48
	s_waitcnt vmcnt(32)
	v_mul_f32_e32 v55, v157, v157
	v_mul_f32_e32 v90, v159, v159
	s_waitcnt vmcnt(31)
	v_mul_f32_e32 v93, v161, v161
	v_mul_f32_e32 v94, v163, v163
	s_waitcnt vmcnt(30)
	v_mul_f32_e32 v97, v165, v165
	v_mul_f32_e32 v98, v167, v167
	v_fmac_f32_e32 v55, v156, v156
	v_fmac_f32_e32 v90, v158, v158
	v_fmac_f32_e32 v93, v160, v160
	v_fmac_f32_e32 v94, v162, v162
	v_mul_f32_e32 v91, v2, v156
	v_mul_f32_e32 v157, v3, v157
	v_mul_f32_e32 v92, v4, v158
	v_mul_f32_e32 v159, v5, v159
	s_waitcnt vmcnt(29)
	v_mul_f32_e32 v101, v169, v169
	v_mul_f32_e32 v102, v171, v171
	v_fmac_f32_e32 v97, v164, v164
	v_fmac_f32_e32 v98, v166, v166
	v_cvt_pk_bf16_f32 v156, v91, v157
	v_add_f32_e32 v55, v55, v90
	v_add_f32_e32 v158, v93, v94
	v_mul_f32_e32 v95, v6, v160
	v_mul_f32_e32 v161, v7, v161
	s_waitcnt vmcnt(28)
	v_mul_f32_e32 v105, v173, v173
	v_mul_f32_e32 v106, v175, v175
	v_fmac_f32_e32 v101, v168, v168
	v_fmac_f32_e32 v102, v170, v170
	v_cvt_pk_bf16_f32 v157, v92, v159
	global_store_dwordx2 v[88:89], v[156:157], off
	v_cvt_pk_bf16_f32 v156, v95, v161
	v_add_f32_e32 v159, v97, v98
	v_add_f32_e32 v55, v55, v158
	v_mul_f32_e32 v96, v8, v162
	v_mul_f32_e32 v163, v9, v163
	v_mul_f32_e32 v99, v10, v164
	v_mul_f32_e32 v165, v11, v165
	s_waitcnt vmcnt(28)
; __device__ __forceinline__ unsigned cvt_pk_bf16(float lo, float hi) { unsigned r; asm volatile("v_cvt_pk_bf16_f32 %0, %1, %2" : "=v"(r) : "v"(lo), "v"(hi)); return r; }
; __device__ void phase_prep(float* ldsf) {
;     ...
;     for (int row = blockIdx.x * 8 + wave; row < M_TOK; row += gridDim.x * 8) {
;         const float4* xr = (const float4*)(x + (size_t)row * DM);
;         float4 xv[8];
; #pragma unroll
;         for (int i = 0; i < 8; ++i) xv[i] = xr[i * 64 + lane];
;         float ss = 0.f;
; #pragma unroll
;         for (int i = 0; i < 8; ++i) { const int idx = i * 64 + lane; const float4 v = xv[i];
;             ss += (v.x * v.x + v.y * v.y) + (v.z * v.z + v.w * v.w);
;             u32x2 w; w.x = cvt_pk_bf16(v.x * gq[i].x, v.y * gq[i].y); w.y = cvt_pk_bf16(v.z * gq[i].z, v.w * gq[i].w);
;             *(u32x2*)(hbf + (size_t)row * DM + idx * 4) = w; }
; #pragma unroll
;         for (int o = 32; o >= 1; o >>= 1) ss += __shfl_xor(ss, o);
;         if (lane == 0) rowss[row] = ss;
	v_mul_f32_e32 v109, v177, v177
	v_mul_f32_e32 v110, v179, v179
	v_fmac_f32_e32 v105, v172, v172
	v_fmac_f32_e32 v106, v174, v174
	v_cvt_pk_bf16_f32 v157, v96, v163
	v_add_f32_e32 v160, v101, v102
	global_store_dwordx2 v[88:89], v[156:157], off offset:512
	v_cvt_pk_bf16_f32 v156, v99, v165
	v_add_f32_e32 v55, v55, v159
	v_mul_f32_e32 v100, v12, v166
	v_mul_f32_e32 v167, v13, v167
	v_mul_f32_e32 v103, v14, v168
	v_mul_f32_e32 v169, v15, v169
	s_waitcnt vmcnt(28)
	v_mul_f32_e32 v111, v181, v181
	v_mul_f32_e32 v112, v183, v183
	v_fmac_f32_e32 v109, v176, v176
	v_fmac_f32_e32 v110, v178, v178
	v_add_f32_e32 v161, v105, v106
	v_cvt_pk_bf16_f32 v157, v100, v167
	global_store_dwordx2 v[88:89], v[156:157], off offset:1024
	v_cvt_pk_bf16_f32 v156, v103, v169
	v_add_f32_e32 v55, v55, v160
	v_mul_f32_e32 v104, v16, v170
	v_mul_f32_e32 v171, v17, v171
	s_waitcnt vmcnt(28)
	v_mul_f32_e32 v113, v185, v185
	v_fmac_f32_e32 v111, v180, v180
	v_fmac_f32_e32 v112, v182, v182
	v_add_f32_e32 v162, v109, v110
	v_cvt_pk_bf16_f32 v157, v104, v171
	global_store_dwordx2 v[88:89], v[156:157], off offset:1536
	v_add_f32_e32 v55, v55, v161
	v_mul_f32_e32 v156, v187, v187
	v_fmac_f32_e32 v113, v184, v184
	v_add_f32_e32 v163, v111, v112
	v_add_f32_e32 v55, v55, v162
	v_fmac_f32_e32 v156, v186, v186
	v_add_f32_e32 v55, v55, v163
	v_add_f32_e32 v156, v113, v156
	v_add_f32_e32 v55, v55, v156
	v_cndmask_b32_e64 v156, v1, v49, s[4:5]
	v_lshlrev_b32_e32 v156, 2, v156
	ds_bpermute_b32 v158, v156, v55
	v_mul_f32_e32 v107, v18, v172
	v_mul_f32_e32 v173, v19, v173
	v_mul_f32_e32 v108, v20, v174
	v_mul_f32_e32 v175, v21, v175
	v_cvt_pk_bf16_f32 v156, v107, v173
	v_cvt_pk_bf16_f32 v157, v108, v175
	v_cmp_lt_i32_e64 s[4:5], v50, v48
	global_store_dwordx2 v[88:89], v[156:157], off offset:2048
	s_waitcnt lgkmcnt(0)
	v_add_f32_e32 v55, v55, v158
	v_cndmask_b32_e64 v157, v1, v50, s[4:5]
	v_lshlrev_b32_e32 v157, 2, v157
	ds_bpermute_b32 v157, v157, v55
	v_cmp_lt_i32_e64 s[4:5], v51, v48
	v_mul_f32_e32 v156, v22, v176
	v_mul_f32_e32 v158, v23, v177
	v_cvt_pk_bf16_f32 v156, v156, v158
	s_waitcnt lgkmcnt(0)
	v_add_f32_e32 v55, v55, v157
	v_cndmask_b32_e64 v157, v1, v51, s[4:5]
	v_lshlrev_b32_e32 v157, 2, v157
	ds_bpermute_b32 v160, v157, v55
	v_mul_f32_e32 v158, v24, v178
	v_cmp_lt_i32_e64 s[4:5], v52, v48
	v_mul_f32_e32 v159, v25, v179
	v_cvt_pk_bf16_f32 v157, v158, v159
	s_waitcnt lgkmcnt(0)
	v_add_f32_e32 v55, v55, v160
	v_cndmask_b32_e64 v158, v1, v52, s[4:5]
	v_lshlrev_b32_e32 v158, 2, v158
	ds_bpermute_b32 v158, v158, v55
	v_cmp_lt_i32_e64 s[4:5], v53, v48
	global_store_dwordx2 v[88:89], v[156:157], off offset:2560
	v_mul_f32_e32 v156, v26, v180
	v_mul_f32_e32 v157, v27, v181
	s_waitcnt lgkmcnt(0)
	v_add_f32_e32 v55, v55, v158
	v_cndmask_b32_e64 v158, v1, v53, s[4:5]
	v_cvt_pk_bf16_f32 v156, v156, v157
	v_mul_f32_e32 v157, v28, v182
	v_mul_f32_e32 v159, v29, v183
	v_lshlrev_b32_e32 v158, 2, v158
	v_cvt_pk_bf16_f32 v157, v157, v159
	ds_bpermute_b32 v159, v158, v55
	global_store_dwordx2 v[88:89], v[156:157], off offset:3072
	v_mul_f32_e32 v156, v30, v184
	v_cmp_lt_i32_e64 s[4:5], v54, v48
	v_mul_f32_e32 v157, v31, v185
	v_cvt_pk_bf16_f32 v158, v156, v157
	s_waitcnt lgkmcnt(0)
	v_add_f32_e32 v55, v55, v159
	v_cndmask_b32_e64 v156, v1, v54, s[4:5]
	v_lshlrev_b32_e32 v156, 2, v156
	ds_bpermute_b32 v156, v156, v55
	v_mul_f32_e32 v159, v33, v187
	v_mul_f32_e32 v157, v32, v186
	v_cvt_pk_bf16_f32 v159, v157, v159
	global_store_dwordx2 v[88:89], v[158:159], off offset:3584
	s_and_saveexec_b64 s[4:5], vcc
	v_lshl_add_u64 v[158:159], v[222:223], 2, s[6:7]
	s_waitcnt lgkmcnt(0)
	v_add_f32_e32 v35, v55, v156
	global_store_dword v[158:159], v35, off
	s_or_b64 exec, exec, s[4:5]
	v_add_u32_e32 v222, 0x1000, v34
	v_mov_b32_e32 v223, 0
	v_lshlrev_b64 v[88:89], 12, v[222:223]
	v_lshl_add_u64 v[88:89], v[38:39], 0, v[88:89]
	v_cmp_lt_i32_e64 s[4:5], v49, v48
	s_waitcnt vmcnt(33)
	v_mul_f32_e32 v55, v189, v189
	v_mul_f32_e32 v90, v191, v191
	s_waitcnt vmcnt(32)
	v_mul_f32_e32 v93, v193, v193
	v_mul_f32_e32 v94, v195, v195
	s_waitcnt vmcnt(31)
	v_mul_f32_e32 v97, v197, v197
	v_mul_f32_e32 v98, v199, v199
	v_fmac_f32_e32 v55, v188, v188
	v_fmac_f32_e32 v90, v190, v190
	v_fmac_f32_e32 v93, v192, v192
	v_fmac_f32_e32 v94, v194, v194
	v_mul_f32_e32 v91, v2, v188
	v_mul_f32_e32 v189, v3, v189
	v_mul_f32_e32 v92, v4, v190
	v_mul_f32_e32 v191, v5, v191
	s_waitcnt vmcnt(30)
	v_mul_f32_e32 v101, v201, v201
	v_mul_f32_e32 v102, v203, v203
	v_fmac_f32_e32 v97, v196, v196
	v_fmac_f32_e32 v98, v198, v198
	v_cvt_pk_bf16_f32 v188, v91, v189
	v_add_f32_e32 v55, v55, v90
	v_add_f32_e32 v190, v93, v94
	v_mul_f32_e32 v95, v6, v192
	v_mul_f32_e32 v193, v7, v193
	s_waitcnt vmcnt(29)
	v_mul_f32_e32 v105, v205, v205
	v_mul_f32_e32 v106, v207, v207
	v_fmac_f32_e32 v101, v200, v200
	v_fmac_f32_e32 v102, v202, v202
	v_cvt_pk_bf16_f32 v189, v92, v191
	global_store_dwordx2 v[88:89], v[188:189], off
	v_cvt_pk_bf16_f32 v188, v95, v193
	v_add_f32_e32 v191, v97, v98
	v_add_f32_e32 v55, v55, v190
	v_mul_f32_e32 v96, v8, v194
	v_mul_f32_e32 v195, v9, v195
	v_mul_f32_e32 v99, v10, v196
	v_mul_f32_e32 v197, v11, v197
	s_waitcnt vmcnt(29)
	v_mul_f32_e32 v109, v209, v209
	v_mul_f32_e32 v110, v211, v211
	v_fmac_f32_e32 v105, v204, v204
	v_fmac_f32_e32 v106, v206, v206
	v_cvt_pk_bf16_f32 v189, v96, v195
	v_add_f32_e32 v192, v101, v102
	global_store_dwordx2 v[88:89], v[188:189], off offset:512
	v_cvt_pk_bf16_f32 v188, v99, v197
	v_add_f32_e32 v55, v55, v191
	v_mul_f32_e32 v100, v12, v198
	v_mul_f32_e32 v199, v13, v199
	v_mul_f32_e32 v103, v14, v200
	v_mul_f32_e32 v201, v15, v201
	s_waitcnt vmcnt(29)
; __device__ __forceinline__ unsigned cvt_pk_bf16(float lo, float hi) { unsigned r; asm volatile("v_cvt_pk_bf16_f32 %0, %1, %2" : "=v"(r) : "v"(lo), "v"(hi)); return r; }
; __device__ void phase_prep(float* ldsf) {
;     ...
;     for (int row = blockIdx.x * 8 + wave; row < M_TOK; row += gridDim.x * 8) {
;         const float4* xr = (const float4*)(x + (size_t)row * DM);
;         float4 xv[8];
; #pragma unroll
;         for (int i = 0; i < 8; ++i) xv[i] = xr[i * 64 + lane];
;         float ss = 0.f;
; #pragma unroll
;         for (int i = 0; i < 8; ++i) { const int idx = i * 64 + lane; const float4 v = xv[i];
;             ss += (v.x * v.x + v.y * v.y) + (v.z * v.z + v.w * v.w);
;             u32x2 w; w.x = cvt_pk_bf16(v.x * gq[i].x, v.y * gq[i].y); w.y = cvt_pk_bf16(v.z * gq[i].z, v.w * gq[i].w);
;             *(u32x2*)(hbf + (size_t)row * DM + idx * 4) = w; }
; #pragma unroll
;         for (int o = 32; o >= 1; o >>= 1) ss += __shfl_xor(ss, o);
;         if (lane == 0) rowss[row] = ss;
	v_mul_f32_e32 v111, v213, v213
	v_mul_f32_e32 v112, v215, v215
	v_fmac_f32_e32 v109, v208, v208
	v_fmac_f32_e32 v110, v210, v210
	v_add_f32_e32 v193, v105, v106
	v_cvt_pk_bf16_f32 v189, v100, v199
	global_store_dwordx2 v[88:89], v[188:189], off offset:1024
	v_cvt_pk_bf16_f32 v188, v103, v201
	v_add_f32_e32 v55, v55, v192
	v_mul_f32_e32 v104, v16, v202
	v_mul_f32_e32 v203, v17, v203
	s_waitcnt vmcnt(29)
	v_mul_f32_e32 v113, v217, v217
	v_fmac_f32_e32 v111, v212, v212
	v_fmac_f32_e32 v112, v214, v214
	v_add_f32_e32 v194, v109, v110
	v_cvt_pk_bf16_f32 v189, v104, v203
	global_store_dwordx2 v[88:89], v[188:189], off offset:1536
	v_add_f32_e32 v55, v55, v193
	v_mul_f32_e32 v188, v219, v219
	v_fmac_f32_e32 v113, v216, v216
	v_add_f32_e32 v195, v111, v112
	v_add_f32_e32 v55, v55, v194
	v_fmac_f32_e32 v188, v218, v218
	v_add_f32_e32 v55, v55, v195
	v_add_f32_e32 v188, v113, v188
	v_add_f32_e32 v55, v55, v188
	v_cndmask_b32_e64 v188, v1, v49, s[4:5]
	v_lshlrev_b32_e32 v188, 2, v188
	ds_bpermute_b32 v190, v188, v55
	v_mul_f32_e32 v107, v18, v204
	v_mul_f32_e32 v205, v19, v205
	v_mul_f32_e32 v108, v20, v206
	v_mul_f32_e32 v207, v21, v207
	v_cvt_pk_bf16_f32 v188, v107, v205
	v_cvt_pk_bf16_f32 v189, v108, v207
	v_cmp_lt_i32_e64 s[4:5], v50, v48
	global_store_dwordx2 v[88:89], v[188:189], off offset:2048
	s_waitcnt lgkmcnt(0)
	v_add_f32_e32 v55, v55, v190
	v_cndmask_b32_e64 v189, v1, v50, s[4:5]
	v_lshlrev_b32_e32 v189, 2, v189
	ds_bpermute_b32 v189, v189, v55
	v_cmp_lt_i32_e64 s[4:5], v51, v48
	v_mul_f32_e32 v188, v22, v208
	v_mul_f32_e32 v190, v23, v209
	v_cvt_pk_bf16_f32 v188, v188, v190
	s_waitcnt lgkmcnt(0)
	v_add_f32_e32 v55, v55, v189
	v_cndmask_b32_e64 v189, v1, v51, s[4:5]
	v_lshlrev_b32_e32 v189, 2, v189
	ds_bpermute_b32 v192, v189, v55
	v_mul_f32_e32 v190, v24, v210
	v_cmp_lt_i32_e64 s[4:5], v52, v48
	v_mul_f32_e32 v191, v25, v211
	v_cvt_pk_bf16_f32 v189, v190, v191
	s_waitcnt lgkmcnt(0)
	v_add_f32_e32 v55, v55, v192
	v_cndmask_b32_e64 v190, v1, v52, s[4:5]
	v_lshlrev_b32_e32 v190, 2, v190
	ds_bpermute_b32 v190, v190, v55
	v_cmp_lt_i32_e64 s[4:5], v53, v48
	global_store_dwordx2 v[88:89], v[188:189], off offset:2560
	v_mul_f32_e32 v188, v26, v212
	v_mul_f32_e32 v189, v27, v213
	s_waitcnt lgkmcnt(0)
	v_add_f32_e32 v55, v55, v190
	v_cndmask_b32_e64 v190, v1, v53, s[4:5]
	v_cvt_pk_bf16_f32 v188, v188, v189
	v_mul_f32_e32 v189, v28, v214
	v_mul_f32_e32 v191, v29, v215
	v_lshlrev_b32_e32 v190, 2, v190
	v_cvt_pk_bf16_f32 v189, v189, v191
	ds_bpermute_b32 v191, v190, v55
	global_store_dwordx2 v[88:89], v[188:189], off offset:3072
	v_mul_f32_e32 v188, v30, v216
	v_cmp_lt_i32_e64 s[4:5], v54, v48
	v_mul_f32_e32 v189, v31, v217
	v_cvt_pk_bf16_f32 v190, v188, v189
	s_waitcnt lgkmcnt(0)
	v_add_f32_e32 v55, v55, v191
	v_cndmask_b32_e64 v188, v1, v54, s[4:5]
	v_lshlrev_b32_e32 v188, 2, v188
	ds_bpermute_b32 v188, v188, v55
	v_mul_f32_e32 v191, v33, v219
	v_mul_f32_e32 v189, v32, v218
	v_cvt_pk_bf16_f32 v191, v189, v191
	global_store_dwordx2 v[88:89], v[190:191], off offset:3584
	s_and_saveexec_b64 s[4:5], vcc
	v_lshl_add_u64 v[190:191], v[222:223], 2, s[6:7]
	s_waitcnt lgkmcnt(0)
	v_add_f32_e32 v35, v55, v188
	global_store_dword v[190:191], v35, off
	s_or_b64 exec, exec, s[4:5]
	v_add_u32_e32 v222, 0x1800, v34
	v_mov_b32_e32 v223, 0
	v_lshlrev_b64 v[88:89], 12, v[222:223]
	v_lshl_add_u64 v[88:89], v[38:39], 0, v[88:89]
	v_cmp_lt_i32_e64 s[4:5], v49, v48
	s_waitcnt vmcnt(25)
	v_mul_f32_e32 v55, v57, v57
	v_mul_f32_e32 v90, v59, v59
	s_waitcnt vmcnt(24)
	v_mul_f32_e32 v93, v61, v61
	v_mul_f32_e32 v94, v63, v63
	s_waitcnt vmcnt(23)
	v_mul_f32_e32 v97, v65, v65
	v_mul_f32_e32 v98, v67, v67
	v_fmac_f32_e32 v55, v56, v56
	v_fmac_f32_e32 v90, v58, v58
	v_fmac_f32_e32 v93, v60, v60
	v_fmac_f32_e32 v94, v62, v62
	v_mul_f32_e32 v91, v2, v56
	v_mul_f32_e32 v57, v3, v57
	v_mul_f32_e32 v92, v4, v58
	v_mul_f32_e32 v59, v5, v59
	s_waitcnt vmcnt(22)
	v_mul_f32_e32 v101, v69, v69
	v_mul_f32_e32 v102, v71, v71
	v_fmac_f32_e32 v97, v64, v64
	v_fmac_f32_e32 v98, v66, v66
	v_cvt_pk_bf16_f32 v56, v91, v57
	v_add_f32_e32 v55, v55, v90
	v_add_f32_e32 v58, v93, v94
	v_mul_f32_e32 v95, v6, v60
	v_mul_f32_e32 v61, v7, v61
	s_waitcnt vmcnt(21)
; __device__ __forceinline__ unsigned cvt_pk_bf16(float lo, float hi) { unsigned r; asm volatile("v_cvt_pk_bf16_f32 %0, %1, %2" : "=v"(r) : "v"(lo), "v"(hi)); return r; }
; __device__ void phase_prep(float* ldsf) {
;     ...
;     for (int row = blockIdx.x * 8 + wave; row < M_TOK; row += gridDim.x * 8) {
;         const float4* xr = (const float4*)(x + (size_t)row * DM);
;         float4 xv[8];
; #pragma unroll
;         for (int i = 0; i < 8; ++i) xv[i] = xr[i * 64 + lane];
;         float ss = 0.f;
; #pragma unroll
;         for (int i = 0; i < 8; ++i) { const int idx = i * 64 + lane; const float4 v = xv[i];
;             ss += (v.x * v.x + v.y * v.y) + (v.z * v.z + v.w * v.w);
;             u32x2 w; w.x = cvt_pk_bf16(v.x * gq[i].x, v.y * gq[i].y); w.y = cvt_pk_bf16(v.z * gq[i].z, v.w * gq[i].w);
;             *(u32x2*)(hbf + (size_t)row * DM + idx * 4) = w; }
; #pragma unroll
;         for (int o = 32; o >= 1; o >>= 1) ss += __shfl_xor(ss, o);
;         if (lane == 0) rowss[row] = ss;
	v_mul_f32_e32 v105, v73, v73
	v_mul_f32_e32 v106, v75, v75
	v_fmac_f32_e32 v101, v68, v68
	v_fmac_f32_e32 v102, v70, v70
	v_cvt_pk_bf16_f32 v57, v92, v59
	global_store_dwordx2 v[88:89], v[56:57], off
	v_cvt_pk_bf16_f32 v56, v95, v61
	v_add_f32_e32 v59, v97, v98
	v_add_f32_e32 v55, v55, v58
	v_mul_f32_e32 v96, v8, v62
	v_mul_f32_e32 v63, v9, v63
	v_mul_f32_e32 v99, v10, v64
	v_mul_f32_e32 v65, v11, v65
	s_waitcnt vmcnt(21)
	v_mul_f32_e32 v109, v77, v77
	v_mul_f32_e32 v110, v79, v79
	v_fmac_f32_e32 v105, v72, v72
	v_fmac_f32_e32 v106, v74, v74
	v_cvt_pk_bf16_f32 v57, v96, v63
	v_add_f32_e32 v60, v101, v102
	global_store_dwordx2 v[88:89], v[56:57], off offset:512
	v_cvt_pk_bf16_f32 v56, v99, v65
	v_add_f32_e32 v55, v55, v59
	v_mul_f32_e32 v100, v12, v66
	v_mul_f32_e32 v67, v13, v67
	v_mul_f32_e32 v103, v14, v68
	v_mul_f32_e32 v69, v15, v69
	s_waitcnt vmcnt(21)
	v_mul_f32_e32 v111, v81, v81
	v_mul_f32_e32 v112, v83, v83
	v_fmac_f32_e32 v109, v76, v76
	v_fmac_f32_e32 v110, v78, v78
	v_add_f32_e32 v61, v105, v106
	v_cvt_pk_bf16_f32 v57, v100, v67
	global_store_dwordx2 v[88:89], v[56:57], off offset:1024
	v_cvt_pk_bf16_f32 v56, v103, v69
	v_add_f32_e32 v55, v55, v60
	v_mul_f32_e32 v104, v16, v70
	v_mul_f32_e32 v71, v17, v71
	s_waitcnt vmcnt(21)
	v_mul_f32_e32 v113, v85, v85
	v_fmac_f32_e32 v111, v80, v80
	v_fmac_f32_e32 v112, v82, v82
	v_add_f32_e32 v62, v109, v110
	v_cvt_pk_bf16_f32 v57, v104, v71
	global_store_dwordx2 v[88:89], v[56:57], off offset:1536
	v_add_f32_e32 v55, v55, v61
	v_mul_f32_e32 v56, v87, v87
	v_fmac_f32_e32 v113, v84, v84
	v_add_f32_e32 v63, v111, v112
	v_add_f32_e32 v55, v55, v62
	v_fmac_f32_e32 v56, v86, v86
	v_add_f32_e32 v55, v55, v63
	v_add_f32_e32 v56, v113, v56
	v_add_f32_e32 v55, v55, v56
	v_cndmask_b32_e64 v56, v1, v49, s[4:5]
	v_lshlrev_b32_e32 v56, 2, v56
	ds_bpermute_b32 v58, v56, v55
	v_mul_f32_e32 v107, v18, v72
	v_mul_f32_e32 v73, v19, v73
	v_mul_f32_e32 v108, v20, v74
	v_mul_f32_e32 v75, v21, v75
	v_cvt_pk_bf16_f32 v56, v107, v73
	v_cvt_pk_bf16_f32 v57, v108, v75
	v_cmp_lt_i32_e64 s[4:5], v50, v48
	global_store_dwordx2 v[88:89], v[56:57], off offset:2048
	s_waitcnt lgkmcnt(0)
	v_add_f32_e32 v55, v55, v58
	v_cndmask_b32_e64 v57, v1, v50, s[4:5]
	v_lshlrev_b32_e32 v57, 2, v57
	ds_bpermute_b32 v57, v57, v55
	v_cmp_lt_i32_e64 s[4:5], v51, v48
	v_mul_f32_e32 v56, v22, v76
	v_mul_f32_e32 v58, v23, v77
	v_cvt_pk_bf16_f32 v56, v56, v58
	s_waitcnt lgkmcnt(0)
	v_add_f32_e32 v55, v55, v57
	v_cndmask_b32_e64 v57, v1, v51, s[4:5]
	v_lshlrev_b32_e32 v57, 2, v57
	ds_bpermute_b32 v60, v57, v55
	v_mul_f32_e32 v58, v24, v78
	v_cmp_lt_i32_e64 s[4:5], v52, v48
	v_mul_f32_e32 v59, v25, v79
	v_cvt_pk_bf16_f32 v57, v58, v59
	s_waitcnt lgkmcnt(0)
	v_add_f32_e32 v55, v55, v60
	v_cndmask_b32_e64 v58, v1, v52, s[4:5]
	v_lshlrev_b32_e32 v58, 2, v58
	ds_bpermute_b32 v58, v58, v55
	v_cmp_lt_i32_e64 s[4:5], v53, v48
	global_store_dwordx2 v[88:89], v[56:57], off offset:2560
	v_mul_f32_e32 v56, v26, v80
	v_mul_f32_e32 v57, v27, v81
	s_waitcnt lgkmcnt(0)
	v_add_f32_e32 v55, v55, v58
	v_cndmask_b32_e64 v58, v1, v53, s[4:5]
	v_cvt_pk_bf16_f32 v56, v56, v57
	v_mul_f32_e32 v57, v28, v82
	v_mul_f32_e32 v59, v29, v83
	v_lshlrev_b32_e32 v58, 2, v58
	v_cvt_pk_bf16_f32 v57, v57, v59
	ds_bpermute_b32 v59, v58, v55
	global_store_dwordx2 v[88:89], v[56:57], off offset:3072
	v_mul_f32_e32 v56, v30, v84
	v_cmp_lt_i32_e64 s[4:5], v54, v48
	v_mul_f32_e32 v57, v31, v85
	v_cvt_pk_bf16_f32 v58, v56, v57
	s_waitcnt lgkmcnt(0)
	v_add_f32_e32 v55, v55, v59
	v_cndmask_b32_e64 v56, v1, v54, s[4:5]
	v_lshlrev_b32_e32 v56, 2, v56
	ds_bpermute_b32 v56, v56, v55
	v_mul_f32_e32 v59, v33, v87
	v_mul_f32_e32 v57, v32, v86
	v_cvt_pk_bf16_f32 v59, v57, v59
	global_store_dwordx2 v[88:89], v[58:59], off offset:3584
	s_and_saveexec_b64 s[4:5], vcc
	v_lshl_add_u64 v[58:59], v[222:223], 2, s[6:7]
	s_waitcnt lgkmcnt(0)
	v_add_f32_e32 v35, v55, v56
	global_store_dword v[58:59], v35, off
	s_or_b64 exec, exec, s[4:5]
	s_branch .LBB0_83
	s_nop 0
	s_nop 0
	s_nop 0
	s_nop 0
	s_nop 0
	s_nop 0
	s_nop 0
	s_nop 0
	s_nop 0
	s_nop 0
	s_nop 0
	s_nop 0
	s_nop 0
	s_nop 0
	s_nop 0
	s_nop 0
	s_nop 0
	s_nop 0
